# v22: GEMM3a K-loop touches the ratio-tile lines needed first (ai=0 rows) in the last four iterations before the mid/epilogue loads (L2 prefetch, reversed order)
# speedup vs baseline: 1.0041x; 1.0041x over previous
; #define PG8_STAGE(bufoff, gbase, voff) do { _Pragma("unroll") for (int _i = 0; _i < 2; ++_i) \
;         __builtin_amdgcn_global_load_lds((const unsigned*)((const char*)(gbase) + (voff)[_i]), (LAS unsigned*)(lds + (bufoff) + ldsw + _i * 8192), 16, 0, 0); } while (0)
; #define PG8_WAIT_V(n) asm volatile("s_waitcnt vmcnt(" #n ")" ::: "memory")
; #define PG8_BAR __builtin_amdgcn_s_barrier()
; template <class Epi>
; __device__ __forceinline__ void gemm_phase(LAS unsigned char* lds, const Gemm g, const StaticOrder& S, const Epi& E) {
;     ...
;         for (int hf = 0; hf < nh; ++hf) {
;         for (int t = hf * nth; t < (hf + 1) * nth; t += 2) {
;             const bool last = (t == nt - 2);
;             const char* a1 = cA + (size_t)(t + 1) * kstep;
;             const char* a2 = last ? nA : cA + (size_t)(t + 2) * kstep; const char* b2 = last ? nB : cB + (size_t)(t + 2) * kstep;
;             const char* a3 = a2 + kstep; const char* b3 = b2 + kstep;
;             PG8_LDB(B0, 0, 0); PG8_LDB(B1, 0, 1); PG8_SCHED; PG8_LDA(At, 0, 0); PG8_STAGE(PG8_SA(1, 1), a1 + hstepA, voffA);
;             PG8_WAIT_V(8); PG8_WAIT_L(0); PG8_BAR; PG8_MMA(0, 0, At, B0); PG8_MMA(0, 1, At, B1); PG8_BAR; PG8_SCHED;
;             PG8_LDA(At, 0, 1); PG8_STAGE(PG8_SB(0, 0), b2, voffB); PG8_STAGE(PG8_SB(0, 1), b2 + hstepB, voffB); PG8_STAGE(PG8_SA(0, 0), a2, voffA);
;             PG8_WAIT_V(8); PG8_WAIT_L(0); PG8_BAR; PG8_MMA(1, 0, At, B0); PG8_MMA(1, 1, At, B1); PG8_BAR; PG8_SCHED;
;             PG8_LDB(B0, 1, 0); PG8_LDB(B1, 1, 1); PG8_SCHED; PG8_LDA(At, 1, 0); PG8_STAGE(PG8_SA(0, 1), a2 + hstepA, voffA);
;             PG8_WAIT_V(8); PG8_WAIT_L(0); PG8_BAR; PG8_MMA(0, 0, At, B0); PG8_MMA(0, 1, At, B1); PG8_BAR; PG8_SCHED;
;             PG8_LDA(At, 1, 1); PG8_STAGE(PG8_SB(1, 0), b3, voffB); PG8_STAGE(PG8_SB(1, 1), b3 + hstepB, voffB); PG8_STAGE(PG8_SA(1, 0), a3, voffA);
;             PG8_WAIT_V(8); PG8_WAIT_L(0); PG8_BAR; PG8_MMA(1, 0, At, B0); PG8_MMA(1, 1, At, B1); PG8_BAR; PG8_SCHED;
;     __device__ __forceinline__ void mid(f32x4 (&acc)[2][2][4][2], const pg8::Unit& u, int wr, int wc, int fr, int fq) const {
;     ...
;             for (int m = 0; m < 4; ++m) { const bf16_t* rowp = (const bf16_t*)((const char*)PJ + (size_t)(boff + (unsigned)((ai * 128 + m * 16) * 2048)));
; #pragma unroll
;                 for (int bj = 0; bj < 2; ++bj) ga[m][bj] = *(const u32x4*)(rowp + T_GA + bj * 128); }
.LBB0_784:
	s_xor_b64 s[30:31], s[34:35], -1
	s_add_i32 s77, s8, 16
	s_lshl_b64 s[36:37], s[8:9], 7
	s_mov_b64 s[46:47], 0xf00
	v_mov_b64_e32 v[2:3], v[192:193]
	v_mov_b64_e32 v[132:133], v[190:191]
	s_mov_b64 s[48:49], s[28:29]
	s_mov_b64 s[50:51], s[26:27]
	s_lshl_b32 s98, s8, 22
	s_add_i32 s98, s98, 0x14040000
	s_mov_b32 s100, 0x8000
	v_mbcnt_lo_u32_b32 v243, -1, 0
	v_mbcnt_hi_u32_b32 v243, -1, v243
	v_lshrrev_b32_e32 v243, 4, v243
	v_lshlrev_b32_e32 v242, 4, v243
	v_sub_u32_e32 v242, v188, v242
	v_and_b32_e32 v243, 1, v243
	v_lshl_add_u32 v242, v243, 8, v242
	v_add_u32_e32 v240, s98, v242
.LBB0_785:
	s_and_b32 s99, s8, 14
	s_cmp_eq_u32 s99, 6
	s_cselect_b32 s99, 0xfffa8000, s100
	v_add_u32_e32 v0, s63, v196
	ds_read_b128 v[134:137], v0
	ds_read_b128 v[138:141], v0 offset:1024
	ds_read_b128 v[142:145], v0 offset:2048
	ds_read_b128 v[146:149], v0 offset:3072
	v_add_u32_e32 v0, s64, v196
	ds_read_b128 v[150:153], v0
	ds_read_b128 v[154:157], v0 offset:1024
	ds_read_b128 v[158:161], v0 offset:2048
	ds_read_b128 v[162:165], v0 offset:3072
	s_add_i32 s8, s8, 2
	s_add_u32 s42, s50, s36
	s_addc_u32 s43, s51, s37
	s_add_u32 s52, s48, s36
	s_addc_u32 s53, s49, s37
	s_cmp_eq_u32 s36, s46
	s_cselect_b32 s43, s21, s43
	s_cselect_b32 s42, s75, s42
	s_cselect_b32 s53, s19, s53
	s_cselect_b32 s52, s76, s52
	v_lshl_add_u64 v[170:171], v[132:133], 0, s[36:37]
	s_add_i32 m0, s55, 0xc000
	ds_read_b128 v[166:169], v198
	ds_read_b128 v[200:203], v198 offset:1024
	ds_read_b128 v[204:207], v198 offset:2048
	ds_read_b128 v[208:211], v198 offset:3072
	ds_read_b128 v[212:215], v198 offset:4096
	ds_read_b128 v[216:219], v198 offset:5120
	ds_read_b128 v[220:223], v198 offset:6144
	ds_read_b128 v[224:227], v198 offset:7168
	global_load_lds_dwordx4 v[170:171], off
	v_lshl_add_u64 v[170:171], v[2:3], 0, s[36:37]
	s_add_i32 m0, s55, 0xe000
	s_nop 0
	global_load_lds_dwordx4 v[170:171], off
	s_waitcnt vmcnt(8)
	s_waitcnt lgkmcnt(0)
	s_barrier
	s_setprio 1
	s_waitcnt lgkmcnt(0)
	v_mfma_f32_16x16x32_bf16 v[128:131], v[134:137], v[166:169], v[128:131]
	v_mfma_f32_16x16x32_bf16 v[124:127], v[142:145], v[166:169], v[124:127]
	v_mfma_f32_16x16x32_bf16 v[112:115], v[134:137], v[204:207], v[112:115]
	v_mfma_f32_16x16x32_bf16 v[108:111], v[142:145], v[204:207], v[108:111]
	v_mfma_f32_16x16x32_bf16 v[96:99], v[134:137], v[212:215], v[96:99]
	v_mfma_f32_16x16x32_bf16 v[92:95], v[142:145], v[212:215], v[92:95]
	v_mfma_f32_16x16x32_bf16 v[80:83], v[134:137], v[220:223], v[80:83]
	v_mfma_f32_16x16x32_bf16 v[76:79], v[142:145], v[220:223], v[76:79]
	v_mfma_f32_16x16x32_bf16 v[128:131], v[138:141], v[200:203], v[128:131]
	v_mfma_f32_16x16x32_bf16 v[124:127], v[146:149], v[200:203], v[124:127]
	v_mfma_f32_16x16x32_bf16 v[112:115], v[138:141], v[208:211], v[112:115]
	v_mfma_f32_16x16x32_bf16 v[108:111], v[146:149], v[208:211], v[108:111]
	v_mfma_f32_16x16x32_bf16 v[96:99], v[138:141], v[216:219], v[96:99]
	v_mfma_f32_16x16x32_bf16 v[92:95], v[146:149], v[216:219], v[92:95]
	v_mfma_f32_16x16x32_bf16 v[80:83], v[138:141], v[224:227], v[80:83]
	v_mfma_f32_16x16x32_bf16 v[76:79], v[146:149], v[224:227], v[76:79]
	s_setprio 0
	s_setprio 1
	v_mfma_f32_16x16x32_bf16 v[120:123], v[150:153], v[166:169], v[120:123]
	v_mfma_f32_16x16x32_bf16 v[116:119], v[158:161], v[166:169], v[116:119]
	v_mfma_f32_16x16x32_bf16 v[104:107], v[150:153], v[204:207], v[104:107]
	v_mfma_f32_16x16x32_bf16 v[100:103], v[158:161], v[204:207], v[100:103]
	v_mfma_f32_16x16x32_bf16 v[88:91], v[150:153], v[212:215], v[88:91]
	v_mfma_f32_16x16x32_bf16 v[84:87], v[158:161], v[212:215], v[84:87]
	v_mfma_f32_16x16x32_bf16 v[72:75], v[150:153], v[220:223], v[72:75]
	v_mfma_f32_16x16x32_bf16 v[68:71], v[158:161], v[220:223], v[68:71]
	v_mfma_f32_16x16x32_bf16 v[120:123], v[154:157], v[200:203], v[120:123]
	v_mfma_f32_16x16x32_bf16 v[116:119], v[162:165], v[200:203], v[116:119]
	v_mfma_f32_16x16x32_bf16 v[104:107], v[154:157], v[208:211], v[104:107]
	v_mfma_f32_16x16x32_bf16 v[100:103], v[162:165], v[208:211], v[100:103]
	v_mfma_f32_16x16x32_bf16 v[88:91], v[154:157], v[216:219], v[88:91]
	v_mfma_f32_16x16x32_bf16 v[84:87], v[162:165], v[216:219], v[84:87]
	v_mfma_f32_16x16x32_bf16 v[72:75], v[154:157], v[224:227], v[72:75]
	v_mfma_f32_16x16x32_bf16 v[68:71], v[162:165], v[224:227], v[68:71]
	s_setprio 0
	s_barrier
	s_add_i32 s78, s63, s54
	v_lshl_add_u64 v[170:171], s[52:53], 0, v[174:175]
	s_mov_b32 m0, s78
	ds_read_b128 v[166:169], v198 offset:16384
	ds_read_b128 v[200:203], v198 offset:17408
	ds_read_b128 v[204:207], v198 offset:18432
	ds_read_b128 v[208:211], v198 offset:19456
	ds_read_b128 v[212:215], v198 offset:20480
	ds_read_b128 v[216:219], v198 offset:21504
	ds_read_b128 v[220:223], v198 offset:22528
	ds_read_b128 v[224:227], v198 offset:23552
	global_load_lds_dwordx4 v[170:171], off
	s_add_i32 m0, s78, 0x2000
	s_add_u32 s78, s52, 0x80000
	v_lshl_add_u64 v[228:229], s[52:53], 0, v[178:179]
	s_addc_u32 s79, s53, 0
	s_add_i32 s80, s64, s54
	global_load_lds_dwordx4 v[228:229], off
	v_lshl_add_u64 v[230:231], s[78:79], 0, v[174:175]
	s_mov_b32 m0, s80
	v_lshl_add_u64 v[232:233], s[42:43], 0, v[176:177]
	global_load_lds_dwordx4 v[230:231], off
	v_lshl_add_u64 v[230:231], s[78:79], 0, v[178:179]
	s_add_i32 m0, s80, 0x2000
	s_nop 0
	global_load_lds_dwordx4 v[230:231], off
	v_lshl_add_u64 v[230:231], s[42:43], 0, v[172:173]
	s_mov_b32 m0, s55
	s_nop 0
	global_load_lds_dwordx4 v[230:231], off
	s_mov_b32 m0, s56
	s_nop 0
	global_load_lds_dwordx4 v[232:233], off
	global_load_dword v241, v240, s[44:45]
	v_add_u32_e32 v240, s99, v240
	s_waitcnt vmcnt(9)
	s_waitcnt lgkmcnt(0)
	s_barrier
; #define PG8_STAGE(bufoff, gbase, voff) do { _Pragma("unroll") for (int _i = 0; _i < 2; ++_i) \
;         __builtin_amdgcn_global_load_lds((const unsigned*)((const char*)(gbase) + (voff)[_i]), (LAS unsigned*)(lds + (bufoff) + ldsw + _i * 8192), 16, 0, 0); } while (0)
; #define PG8_LDA(dst, b, h) do { _Pragma("unroll") for (int m = 0; m < 4; ++m) _Pragma("unroll") for (int k = 0; k < 2; ++k) dst[m][k] = *(const LAS bf16x8*)(lds + PG8_SA(b, h) + aoff + m * 2048 + k * 1024); } while (0)
; #define PG8_LDB(dst, b, h) do { _Pragma("unroll") for (int n = 0; n < 2; ++n) _Pragma("unroll") for (int k = 0; k < 2; ++k) dst[n][k] = *(const LAS bf16x8*)(lds + PG8_SB(b, h) + boff + n * 2048 + k * 1024); } while (0)
; #define PG8_MMA(ai, bj, At, Bt) do { __builtin_amdgcn_s_setprio(1); _Pragma("unroll") for (int m = 0; m < 4; ++m) _Pragma("unroll") for (int n = 0; n < 2; ++n) _Pragma("unroll") for (int k = 0; k < 2; ++k) \
;         acc[ai][bj][m][n] = __builtin_amdgcn_mfma_f32_16x16x32_bf16(Bt[n][k], At[m][k], acc[ai][bj][m][n], 0, 0, 0); __builtin_amdgcn_s_setprio(0); } while (0)
; #define PG8_WAIT_V(n) asm volatile("s_waitcnt vmcnt(" #n ")" ::: "memory")
; #define PG8_BAR __builtin_amdgcn_s_barrier()
; template <class Epi>
; __device__ __forceinline__ void gemm_phase(LAS unsigned char* lds, const Gemm g, const StaticOrder& S, const Epi& E) {
;     ...
;             PG8_LDB(B0, 0, 0); PG8_LDB(B1, 0, 1); PG8_SCHED; PG8_LDA(At, 0, 0); PG8_STAGE(PG8_SA(1, 1), a1 + hstepA, voffA);
;             PG8_WAIT_V(8); PG8_WAIT_L(0); PG8_BAR; PG8_MMA(0, 0, At, B0); PG8_MMA(0, 1, At, B1); PG8_BAR; PG8_SCHED;
;             PG8_LDA(At, 0, 1); PG8_STAGE(PG8_SB(0, 0), b2, voffB); PG8_STAGE(PG8_SB(0, 1), b2 + hstepB, voffB); PG8_STAGE(PG8_SA(0, 0), a2, voffA);
;             PG8_WAIT_V(8); PG8_WAIT_L(0); PG8_BAR; PG8_MMA(1, 0, At, B0); PG8_MMA(1, 1, At, B1); PG8_BAR; PG8_SCHED;
;             PG8_LDB(B0, 1, 0); PG8_LDB(B1, 1, 1); PG8_SCHED; PG8_LDA(At, 1, 0); PG8_STAGE(PG8_SA(0, 1), a2 + hstepA, voffA);
;             PG8_WAIT_V(8); PG8_WAIT_L(0); PG8_BAR; PG8_MMA(0, 0, At, B0); PG8_MMA(0, 1, At, B1); PG8_BAR; PG8_SCHED;
;             PG8_LDA(At, 1, 1); PG8_STAGE(PG8_SB(1, 0), b3, voffB); PG8_STAGE(PG8_SB(1, 1), b3 + hstepB, voffB); PG8_STAGE(PG8_SA(1, 0), a3, voffA);
;             PG8_WAIT_V(8); PG8_WAIT_L(0); PG8_BAR; PG8_MMA(1, 0, At, B0); PG8_MMA(1, 1, At, B1); PG8_BAR; PG8_SCHED;
	s_setprio 1
	s_waitcnt lgkmcnt(0)
	v_mfma_f32_16x16x32_bf16 v[64:67], v[134:137], v[166:169], v[64:67]
	v_mfma_f32_16x16x32_bf16 v[60:63], v[142:145], v[166:169], v[60:63]
	v_mfma_f32_16x16x32_bf16 v[48:51], v[134:137], v[204:207], v[48:51]
	v_mfma_f32_16x16x32_bf16 v[44:47], v[142:145], v[204:207], v[44:47]
	v_mfma_f32_16x16x32_bf16 v[32:35], v[134:137], v[212:215], v[32:35]
	v_mfma_f32_16x16x32_bf16 v[28:31], v[142:145], v[212:215], v[28:31]
	v_mfma_f32_16x16x32_bf16 v[16:19], v[134:137], v[220:223], v[16:19]
	v_mfma_f32_16x16x32_bf16 v[12:15], v[142:145], v[220:223], v[12:15]
	v_mfma_f32_16x16x32_bf16 v[64:67], v[138:141], v[200:203], v[64:67]
	v_mfma_f32_16x16x32_bf16 v[60:63], v[146:149], v[200:203], v[60:63]
	v_mfma_f32_16x16x32_bf16 v[48:51], v[138:141], v[208:211], v[48:51]
	v_mfma_f32_16x16x32_bf16 v[44:47], v[146:149], v[208:211], v[44:47]
	v_mfma_f32_16x16x32_bf16 v[32:35], v[138:141], v[216:219], v[32:35]
	v_mfma_f32_16x16x32_bf16 v[28:31], v[146:149], v[216:219], v[28:31]
	v_mfma_f32_16x16x32_bf16 v[16:19], v[138:141], v[224:227], v[16:19]
	v_mfma_f32_16x16x32_bf16 v[12:15], v[146:149], v[224:227], v[12:15]
	s_setprio 0
	s_setprio 1
	v_mfma_f32_16x16x32_bf16 v[56:59], v[150:153], v[166:169], v[56:59]
	v_mfma_f32_16x16x32_bf16 v[52:55], v[158:161], v[166:169], v[52:55]
	v_mfma_f32_16x16x32_bf16 v[40:43], v[150:153], v[204:207], v[40:43]
	v_mfma_f32_16x16x32_bf16 v[36:39], v[158:161], v[204:207], v[36:39]
	v_mfma_f32_16x16x32_bf16 v[24:27], v[150:153], v[212:215], v[24:27]
	v_mfma_f32_16x16x32_bf16 v[20:23], v[158:161], v[212:215], v[20:23]
	v_mfma_f32_16x16x32_bf16 v[8:11], v[150:153], v[220:223], v[8:11]
	v_mfma_f32_16x16x32_bf16 v[4:7], v[158:161], v[220:223], v[4:7]
	v_mfma_f32_16x16x32_bf16 v[56:59], v[154:157], v[200:203], v[56:59]
	v_mfma_f32_16x16x32_bf16 v[52:55], v[162:165], v[200:203], v[52:55]
	v_mfma_f32_16x16x32_bf16 v[40:43], v[154:157], v[208:211], v[40:43]
	v_mfma_f32_16x16x32_bf16 v[36:39], v[162:165], v[208:211], v[36:39]
	v_mfma_f32_16x16x32_bf16 v[24:27], v[154:157], v[216:219], v[24:27]
	v_mfma_f32_16x16x32_bf16 v[20:23], v[162:165], v[216:219], v[20:23]
	v_mfma_f32_16x16x32_bf16 v[8:11], v[154:157], v[224:227], v[8:11]
	v_mfma_f32_16x16x32_bf16 v[4:7], v[162:165], v[224:227], v[4:7]
	s_setprio 0
	s_barrier
	s_add_i32 s78, 0, 0x18000
	v_add_u32_e32 v0, s78, v196
	s_add_i32 s79, 0, 0x1c000
	ds_read_b128 v[134:137], v0
	ds_read_b128 v[138:141], v0 offset:1024
	ds_read_b128 v[142:145], v0 offset:2048
	ds_read_b128 v[146:149], v0 offset:3072
	v_add_u32_e32 v0, s79, v196
	ds_read_b128 v[150:153], v0
	ds_read_b128 v[154:157], v0 offset:1024
	ds_read_b128 v[158:161], v0 offset:2048
	ds_read_b128 v[162:165], v0 offset:3072
	s_add_u32 s42, s42, 0x80000
	s_addc_u32 s43, s43, 0
	s_mov_b32 m0, s57
	v_lshl_add_u64 v[234:235], s[42:43], 0, v[172:173]
	ds_read_b128 v[166:169], v198 offset:32768
	ds_read_b128 v[200:203], v198 offset:33792
	ds_read_b128 v[204:207], v198 offset:34816
	ds_read_b128 v[208:211], v198 offset:35840
	ds_read_b128 v[212:215], v198 offset:36864
	ds_read_b128 v[216:219], v198 offset:37888
	ds_read_b128 v[220:223], v198 offset:38912
	ds_read_b128 v[224:227], v198 offset:39936
	global_load_lds_dwordx4 v[234:235], off
	v_lshl_add_u64 v[234:235], s[42:43], 0, v[176:177]
	s_mov_b32 m0, s58
	s_nop 0
	global_load_lds_dwordx4 v[234:235], off
	s_waitcnt vmcnt(9)
	s_waitcnt lgkmcnt(0)
	s_barrier
	s_setprio 1
	s_waitcnt lgkmcnt(0)
	v_mfma_f32_16x16x32_bf16 v[128:131], v[134:137], v[166:169], v[128:131]
	v_mfma_f32_16x16x32_bf16 v[124:127], v[142:145], v[166:169], v[124:127]
	v_mfma_f32_16x16x32_bf16 v[112:115], v[134:137], v[204:207], v[112:115]
	v_mfma_f32_16x16x32_bf16 v[108:111], v[142:145], v[204:207], v[108:111]
	v_mfma_f32_16x16x32_bf16 v[96:99], v[134:137], v[212:215], v[96:99]
	v_mfma_f32_16x16x32_bf16 v[92:95], v[142:145], v[212:215], v[92:95]
	v_mfma_f32_16x16x32_bf16 v[80:83], v[134:137], v[220:223], v[80:83]
	v_mfma_f32_16x16x32_bf16 v[76:79], v[142:145], v[220:223], v[76:79]
	v_mfma_f32_16x16x32_bf16 v[128:131], v[138:141], v[200:203], v[128:131]
	v_mfma_f32_16x16x32_bf16 v[124:127], v[146:149], v[200:203], v[124:127]
	v_mfma_f32_16x16x32_bf16 v[112:115], v[138:141], v[208:211], v[112:115]
	v_mfma_f32_16x16x32_bf16 v[108:111], v[146:149], v[208:211], v[108:111]
	v_mfma_f32_16x16x32_bf16 v[96:99], v[138:141], v[216:219], v[96:99]
	v_mfma_f32_16x16x32_bf16 v[92:95], v[146:149], v[216:219], v[92:95]
	v_mfma_f32_16x16x32_bf16 v[80:83], v[138:141], v[224:227], v[80:83]
	v_mfma_f32_16x16x32_bf16 v[76:79], v[146:149], v[224:227], v[76:79]
	s_setprio 0
	s_setprio 1
	v_mfma_f32_16x16x32_bf16 v[120:123], v[150:153], v[166:169], v[120:123]
	v_mfma_f32_16x16x32_bf16 v[116:119], v[158:161], v[166:169], v[116:119]
	v_mfma_f32_16x16x32_bf16 v[104:107], v[150:153], v[204:207], v[104:107]
	v_mfma_f32_16x16x32_bf16 v[100:103], v[158:161], v[204:207], v[100:103]
	v_mfma_f32_16x16x32_bf16 v[88:91], v[150:153], v[212:215], v[88:91]
	v_mfma_f32_16x16x32_bf16 v[84:87], v[158:161], v[212:215], v[84:87]
	v_mfma_f32_16x16x32_bf16 v[72:75], v[150:153], v[220:223], v[72:75]
	v_mfma_f32_16x16x32_bf16 v[68:71], v[158:161], v[220:223], v[68:71]
	v_mfma_f32_16x16x32_bf16 v[120:123], v[154:157], v[200:203], v[120:123]
	v_mfma_f32_16x16x32_bf16 v[116:119], v[162:165], v[200:203], v[116:119]
	v_mfma_f32_16x16x32_bf16 v[104:107], v[154:157], v[208:211], v[104:107]
	v_mfma_f32_16x16x32_bf16 v[100:103], v[162:165], v[208:211], v[100:103]
	v_mfma_f32_16x16x32_bf16 v[88:91], v[154:157], v[216:219], v[88:91]
	v_mfma_f32_16x16x32_bf16 v[84:87], v[162:165], v[216:219], v[84:87]
	v_mfma_f32_16x16x32_bf16 v[72:75], v[154:157], v[224:227], v[72:75]
	v_mfma_f32_16x16x32_bf16 v[68:71], v[162:165], v[224:227], v[68:71]
	s_setprio 0
	s_barrier
; #define PG8_STAGE(bufoff, gbase, voff) do { _Pragma("unroll") for (int _i = 0; _i < 2; ++_i) \
;         __builtin_amdgcn_global_load_lds((const unsigned*)((const char*)(gbase) + (voff)[_i]), (LAS unsigned*)(lds + (bufoff) + ldsw + _i * 8192), 16, 0, 0); } while (0)
; #define PG8_LDA(dst, b, h) do { _Pragma("unroll") for (int m = 0; m < 4; ++m) _Pragma("unroll") for (int k = 0; k < 2; ++k) dst[m][k] = *(const LAS bf16x8*)(lds + PG8_SA(b, h) + aoff + m * 2048 + k * 1024); } while (0)
; #define PG8_WAIT_V(n) asm volatile("s_waitcnt vmcnt(" #n ")" ::: "memory")
; #define PG8_BAR __builtin_amdgcn_s_barrier()
; template <class Epi>
; __device__ __forceinline__ void gemm_phase(LAS unsigned char* lds, const Gemm g, const StaticOrder& S, const Epi& E) {
;     ...
;             PG8_LDB(B0, 0, 0); PG8_LDB(B1, 0, 1); PG8_SCHED; PG8_LDA(At, 0, 0); PG8_STAGE(PG8_SA(1, 1), a1 + hstepA, voffA);
;             PG8_WAIT_V(8); PG8_WAIT_L(0); PG8_BAR; PG8_MMA(0, 0, At, B0); PG8_MMA(0, 1, At, B1); PG8_BAR; PG8_SCHED;
;             PG8_LDA(At, 0, 1); PG8_STAGE(PG8_SB(0, 0), b2, voffB); PG8_STAGE(PG8_SB(0, 1), b2 + hstepB, voffB); PG8_STAGE(PG8_SA(0, 0), a2, voffA);
;             PG8_WAIT_V(8); PG8_WAIT_L(0); PG8_BAR; PG8_MMA(1, 0, At, B0); PG8_MMA(1, 1, At, B1); PG8_BAR; PG8_SCHED;
;             PG8_LDB(B0, 1, 0); PG8_LDB(B1, 1, 1); PG8_SCHED; PG8_LDA(At, 1, 0); PG8_STAGE(PG8_SA(0, 1), a2 + hstepA, voffA);
;             PG8_WAIT_V(8); PG8_WAIT_L(0); PG8_BAR; PG8_MMA(0, 0, At, B0); PG8_MMA(0, 1, At, B1); PG8_BAR; PG8_SCHED;
;             PG8_LDA(At, 1, 1); PG8_STAGE(PG8_SB(1, 0), b3, voffB); PG8_STAGE(PG8_SB(1, 1), b3 + hstepB, voffB); PG8_STAGE(PG8_SA(1, 0), a3, voffA);
;             PG8_WAIT_V(8); PG8_WAIT_L(0); PG8_BAR; PG8_MMA(1, 0, At, B0); PG8_MMA(1, 1, At, B1); PG8_BAR; PG8_SCHED;
;         }
;         if constexpr (Epi::MID) { if (hf == 0) E.mid(acc, cur, wr, wc, fr, fq); }
;         }
;     __device__ __forceinline__ void mid(f32x4 (&acc)[2][2][4][2], const pg8::Unit& u, int wr, int wc, int fr, int fq) const {
;     ...
;         for (int ai = 0; ai < 2; ++ai) {
;             u32x4 ga[4][2];
; #pragma unroll
;             for (int m = 0; m < 4; ++m) { const bf16_t* rowp = (const bf16_t*)((const char*)PJ + (size_t)(boff + (unsigned)((ai * 128 + m * 16) * 2048)));
; #pragma unroll
;                 for (int bj = 0; bj < 2; ++bj) ga[m][bj] = *(const u32x4*)(rowp + T_GA + bj * 128); }
	s_add_i32 s42, s78, s54
	v_lshl_add_u64 v[170:171], v[170:171], 0, s[12:13]
	s_mov_b32 m0, s42
	ds_read_b128 v[166:169], v198 offset:49152
	ds_read_b128 v[200:203], v198 offset:50176
	ds_read_b128 v[204:207], v198 offset:51200
	ds_read_b128 v[208:211], v198 offset:52224
	ds_read_b128 v[212:215], v198 offset:53248
	ds_read_b128 v[216:219], v198 offset:54272
	ds_read_b128 v[220:223], v198 offset:55296
	ds_read_b128 v[224:227], v198 offset:56320
	global_load_lds_dwordx4 v[170:171], off
	s_add_i32 m0, s42, 0x2000
	s_add_u32 s42, s52, 0x80080
	v_lshl_add_u64 v[170:171], v[228:229], 0, s[12:13]
	s_addc_u32 s43, s53, 0
	s_add_i32 s52, s79, s54
	global_load_lds_dwordx4 v[170:171], off
	v_lshl_add_u64 v[170:171], s[42:43], 0, v[174:175]
	s_mov_b32 m0, s52
	s_nop 0
	global_load_lds_dwordx4 v[170:171], off
	v_lshl_add_u64 v[170:171], s[42:43], 0, v[178:179]
	s_add_i32 m0, s52, 0x2000
	s_nop 0
	global_load_lds_dwordx4 v[170:171], off
	v_lshl_add_u64 v[170:171], v[230:231], 0, s[12:13]
	s_mov_b32 m0, s59
	s_nop 0
	global_load_lds_dwordx4 v[170:171], off
	v_lshl_add_u64 v[170:171], v[232:233], 0, s[12:13]
	s_mov_b32 m0, s60
	s_nop 0
	global_load_lds_dwordx4 v[170:171], off
	s_waitcnt vmcnt(9)
	s_waitcnt lgkmcnt(0)
	s_barrier
	s_setprio 1
	s_waitcnt lgkmcnt(0)
	v_mfma_f32_16x16x32_bf16 v[64:67], v[134:137], v[166:169], v[64:67]
	v_mfma_f32_16x16x32_bf16 v[60:63], v[142:145], v[166:169], v[60:63]
	v_mfma_f32_16x16x32_bf16 v[48:51], v[134:137], v[204:207], v[48:51]
	v_mfma_f32_16x16x32_bf16 v[44:47], v[142:145], v[204:207], v[44:47]
	v_mfma_f32_16x16x32_bf16 v[32:35], v[134:137], v[212:215], v[32:35]
	v_mfma_f32_16x16x32_bf16 v[28:31], v[142:145], v[212:215], v[28:31]
	v_mfma_f32_16x16x32_bf16 v[16:19], v[134:137], v[220:223], v[16:19]
	v_mfma_f32_16x16x32_bf16 v[12:15], v[142:145], v[220:223], v[12:15]
	v_mfma_f32_16x16x32_bf16 v[64:67], v[138:141], v[200:203], v[64:67]
	v_mfma_f32_16x16x32_bf16 v[60:63], v[146:149], v[200:203], v[60:63]
	v_mfma_f32_16x16x32_bf16 v[48:51], v[138:141], v[208:211], v[48:51]
	v_mfma_f32_16x16x32_bf16 v[44:47], v[146:149], v[208:211], v[44:47]
	v_mfma_f32_16x16x32_bf16 v[32:35], v[138:141], v[216:219], v[32:35]
	v_mfma_f32_16x16x32_bf16 v[28:31], v[146:149], v[216:219], v[28:31]
	v_mfma_f32_16x16x32_bf16 v[16:19], v[138:141], v[224:227], v[16:19]
	v_mfma_f32_16x16x32_bf16 v[12:15], v[146:149], v[224:227], v[12:15]
	s_setprio 0
	s_setprio 1
	v_mfma_f32_16x16x32_bf16 v[56:59], v[150:153], v[166:169], v[56:59]
	v_mfma_f32_16x16x32_bf16 v[52:55], v[158:161], v[166:169], v[52:55]
	v_mfma_f32_16x16x32_bf16 v[40:43], v[150:153], v[204:207], v[40:43]
	v_mfma_f32_16x16x32_bf16 v[36:39], v[158:161], v[204:207], v[36:39]
	v_mfma_f32_16x16x32_bf16 v[24:27], v[150:153], v[212:215], v[24:27]
	v_mfma_f32_16x16x32_bf16 v[20:23], v[158:161], v[212:215], v[20:23]
	v_mfma_f32_16x16x32_bf16 v[8:11], v[150:153], v[220:223], v[8:11]
	v_mfma_f32_16x16x32_bf16 v[4:7], v[158:161], v[220:223], v[4:7]
	v_mfma_f32_16x16x32_bf16 v[56:59], v[154:157], v[200:203], v[56:59]
	v_mfma_f32_16x16x32_bf16 v[52:55], v[162:165], v[200:203], v[52:55]
	v_mfma_f32_16x16x32_bf16 v[40:43], v[154:157], v[208:211], v[40:43]
	v_mfma_f32_16x16x32_bf16 v[36:39], v[162:165], v[208:211], v[36:39]
	v_mfma_f32_16x16x32_bf16 v[24:27], v[154:157], v[216:219], v[24:27]
	v_mfma_f32_16x16x32_bf16 v[20:23], v[162:165], v[216:219], v[20:23]
	v_mfma_f32_16x16x32_bf16 v[8:11], v[154:157], v[224:227], v[8:11]
	v_mfma_f32_16x16x32_bf16 v[4:7], v[162:165], v[224:227], v[4:7]
	s_setprio 0
	s_barrier
	s_add_u32 s50, s50, 0x100
	s_addc_u32 s51, s51, 0
	s_add_u32 s48, s48, 0x100
	s_addc_u32 s49, s49, 0
	s_add_u32 s46, s46, 0xffffff00
	s_addc_u32 s47, s47, -1
	v_lshl_add_u64 v[132:133], v[132:133], 0, s[16:17]
	s_cmp_ge_u32 s8, s77
	v_lshl_add_u64 v[2:3], v[2:3], 0, s[16:17]
	s_cbranch_scc0 .LBB0_785
	s_and_b64 vcc, exec, s[34:35]
	s_cbranch_vccz .LBB0_783
	v_mov_b32_e32 v0, v188
	s_nop 0
	v_lshl_add_u64 v[2:3], s[44:45], 0, v[0:1]
	v_add_co_u32_e32 v2, vcc, 0x14000000, v2
	s_nop 1
	v_addc_co_u32_e32 v3, vcc, 0, v3, vcc
	global_load_dwordx4 v[160:163], v[2:3], off
	global_load_dwordx4 v[156:159], v[2:3], off offset:256
	v_add_u32_e32 v2, 0x8000, v0
	v_mov_b32_e32 v3, v1
	v_lshl_add_u64 v[2:3], s[44:45], 0, v[2:3]
	v_add_co_u32_e32 v2, vcc, 0x14000000, v2
	s_nop 1
	v_addc_co_u32_e32 v3, vcc, 0, v3, vcc
	global_load_dwordx4 v[152:155], v[2:3], off
	global_load_dwordx4 v[148:151], v[2:3], off offset:256
	v_add_u32_e32 v2, 0x10000, v0
	v_mov_b32_e32 v3, v1
	v_lshl_add_u64 v[2:3], s[44:45], 0, v[2:3]
	v_add_co_u32_e32 v2, vcc, 0x14000000, v2
	s_nop 1
	v_addc_co_u32_e32 v3, vcc, 0, v3, vcc
	global_load_dwordx4 v[144:147], v[2:3], off
	global_load_dwordx4 v[140:143], v[2:3], off offset:256
	v_add_u32_e32 v2, 0x18000, v0
	v_mov_b32_e32 v3, v1
	v_lshl_add_u64 v[2:3], s[44:45], 0, v[2:3]
	v_add_co_u32_e32 v2, vcc, 0x14000000, v2
	s_nop 1
	v_addc_co_u32_e32 v3, vcc, 0, v3, vcc
	global_load_dwordx4 v[136:139], v[2:3], off
	global_load_dwordx4 v[132:135], v[2:3], off offset:256
	s_waitcnt vmcnt(0)
; __device__ __forceinline__ float bflo(unsigned w) { return __uint_as_float(w << 16); }
; __device__ __forceinline__ float bfhi(unsigned w) { return __uint_as_float(w & 0xffff0000u); }
;     __device__ __forceinline__ void mid(f32x4 (&acc)[2][2][4][2], const pg8::Unit& u, int wr, int wc, int fr, int fq) const {
;     ...
;         for (int ai = 0; ai < 2; ++ai) {
;             u32x4 ga[4][2];
; #pragma unroll
;             for (int m = 0; m < 4; ++m) { const bf16_t* rowp = (const bf16_t*)((const char*)PJ + (size_t)(boff + (unsigned)((ai * 128 + m * 16) * 2048)));
; #pragma unroll
;                 for (int bj = 0; bj < 2; ++bj) ga[m][bj] = *(const u32x4*)(rowp + T_GA + bj * 128); }
;             __builtin_amdgcn_sched_barrier(0);
; #pragma unroll
;             for (int m = 0; m < 4; ++m)
; #pragma unroll
;                 for (int bj = 0; bj < 2; ++bj) {
;                     const u32x4 a = ga[m][bj];
;                     acc[ai][bj][m][0] = acc[ai][bj][m][0] * (f32x4){bflo(a.x), bfhi(a.x), bflo(a.y), bfhi(a.y)}; acc[ai][bj][m][1] = acc[ai][bj][m][1] * (f32x4){bflo(a.z), bfhi(a.z), bflo(a.w), bfhi(a.w)};
;                 }
	v_lshlrev_b32_e32 v2, 16, v160
	v_and_b32_e32 v3, 0xffff0000, v160
	v_pk_mul_f32 v[128:129], v[128:129], v[2:3]
	v_lshlrev_b32_e32 v2, 16, v162
	v_and_b32_e32 v3, 0xffff0000, v162
	v_pk_mul_f32 v[124:125], v[124:125], v[2:3]
	v_lshlrev_b32_e32 v2, 16, v156
	v_and_b32_e32 v3, 0xffff0000, v156
	v_lshlrev_b32_e32 v156, 16, v157
	v_and_b32_e32 v157, 0xffff0000, v157
	v_pk_mul_f32 v[122:123], v[122:123], v[156:157]
	v_add_u32_e32 v156, 0x40000, v0
	v_mov_b32_e32 v157, v1
	v_lshl_add_u64 v[156:157], s[44:45], 0, v[156:157]
	v_add_co_u32_e32 v156, vcc, s65, v156
	v_lshlrev_b32_e32 v160, 16, v161
	s_nop 0
	v_addc_co_u32_e32 v157, vcc, 0, v157, vcc
	global_load_dwordx4 v[200:203], v[156:157], off
	global_load_dwordx4 v[204:207], v[156:157], off offset:256
	v_add_u32_e32 v156, 0x48000, v0
	v_mov_b32_e32 v157, v1
	v_lshl_add_u64 v[156:157], s[44:45], 0, v[156:157]
	v_add_co_u32_e32 v156, vcc, s65, v156
	v_and_b32_e32 v161, 0xffff0000, v161
	s_nop 0
	v_addc_co_u32_e32 v157, vcc, 0, v157, vcc
	global_load_dwordx4 v[208:211], v[156:157], off
	global_load_dwordx4 v[212:215], v[156:157], off offset:256
	v_add_u32_e32 v156, 0x50000, v0
	v_mov_b32_e32 v157, v1
	v_lshl_add_u64 v[156:157], s[44:45], 0, v[156:157]
	v_add_co_u32_e32 v156, vcc, s65, v156
	v_add_u32_e32 v0, 0x58000, v0
	s_nop 0
	v_addc_co_u32_e32 v157, vcc, 0, v157, vcc
	global_load_dwordx4 v[216:219], v[156:157], off
	global_load_dwordx4 v[168:171], v[156:157], off offset:256
	v_lshl_add_u64 v[156:157], s[44:45], 0, v[0:1]
	v_add_co_u32_e32 v156, vcc, s65, v156
	v_pk_mul_f32 v[130:131], v[130:131], v[160:161]
	v_lshlrev_b32_e32 v160, 16, v163
	v_and_b32_e32 v161, 0xffff0000, v163
	v_addc_co_u32_e32 v157, vcc, 0, v157, vcc
	v_pk_mul_f32 v[126:127], v[126:127], v[160:161]
	global_load_dwordx4 v[164:167], v[156:157], off
	global_load_dwordx4 v[160:163], v[156:157], off offset:256
	v_pk_mul_f32 v[120:121], v[120:121], v[2:3]
	v_lshlrev_b32_e32 v2, 16, v158
	v_and_b32_e32 v3, 0xffff0000, v158
	v_pk_mul_f32 v[116:117], v[116:117], v[2:3]
	v_lshlrev_b32_e32 v2, 16, v152
	v_and_b32_e32 v3, 0xffff0000, v152
	v_pk_mul_f32 v[112:113], v[112:113], v[2:3]
	v_lshlrev_b32_e32 v2, 16, v154
	v_and_b32_e32 v3, 0xffff0000, v154
	v_pk_mul_f32 v[108:109], v[108:109], v[2:3]
	v_lshlrev_b32_e32 v2, 16, v148
	v_and_b32_e32 v3, 0xffff0000, v148
	v_pk_mul_f32 v[104:105], v[104:105], v[2:3]
	v_lshlrev_b32_e32 v2, 16, v150
	v_and_b32_e32 v3, 0xffff0000, v150
	v_pk_mul_f32 v[100:101], v[100:101], v[2:3]
	v_lshlrev_b32_e32 v2, 16, v144
	v_and_b32_e32 v3, 0xffff0000, v144
	v_pk_mul_f32 v[96:97], v[96:97], v[2:3]
	v_lshlrev_b32_e32 v2, 16, v146
	v_and_b32_e32 v3, 0xffff0000, v146
	v_pk_mul_f32 v[92:93], v[92:93], v[2:3]
	v_lshlrev_b32_e32 v2, 16, v140
	v_and_b32_e32 v3, 0xffff0000, v140
	v_pk_mul_f32 v[88:89], v[88:89], v[2:3]
	v_lshlrev_b32_e32 v2, 16, v142
	v_and_b32_e32 v3, 0xffff0000, v142
	v_pk_mul_f32 v[84:85], v[84:85], v[2:3]
	v_lshlrev_b32_e32 v2, 16, v136
	v_and_b32_e32 v3, 0xffff0000, v136
	v_pk_mul_f32 v[80:81], v[80:81], v[2:3]
	v_lshlrev_b32_e32 v2, 16, v138
	v_and_b32_e32 v3, 0xffff0000, v138
	v_lshlrev_b32_e32 v152, 16, v153
	v_and_b32_e32 v153, 0xffff0000, v153
	v_lshlrev_b32_e32 v148, 16, v149
	v_and_b32_e32 v149, 0xffff0000, v149
	v_lshlrev_b32_e32 v144, 16, v145
	v_and_b32_e32 v145, 0xffff0000, v145
	v_lshlrev_b32_e32 v140, 16, v141
	v_and_b32_e32 v141, 0xffff0000, v141
	v_lshlrev_b32_e32 v136, 16, v137
	v_and_b32_e32 v137, 0xffff0000, v137
	v_pk_mul_f32 v[76:77], v[76:77], v[2:3]
	v_lshlrev_b32_e32 v2, 16, v132
	v_and_b32_e32 v3, 0xffff0000, v132
	v_lshlrev_b32_e32 v132, 16, v133
	v_and_b32_e32 v133, 0xffff0000, v133
	v_lshlrev_b32_e32 v156, 16, v159
	v_and_b32_e32 v157, 0xffff0000, v159
	v_pk_mul_f32 v[114:115], v[114:115], v[152:153]
	v_lshlrev_b32_e32 v152, 16, v155
	v_and_b32_e32 v153, 0xffff0000, v155
	v_pk_mul_f32 v[106:107], v[106:107], v[148:149]
	v_lshlrev_b32_e32 v148, 16, v151
	v_and_b32_e32 v149, 0xffff0000, v151
	v_pk_mul_f32 v[98:99], v[98:99], v[144:145]
	v_lshlrev_b32_e32 v144, 16, v147
	v_and_b32_e32 v145, 0xffff0000, v147
	v_pk_mul_f32 v[90:91], v[90:91], v[140:141]
	v_lshlrev_b32_e32 v140, 16, v143
	v_and_b32_e32 v141, 0xffff0000, v143
	v_pk_mul_f32 v[82:83], v[82:83], v[136:137]
	v_lshlrev_b32_e32 v136, 16, v139
	v_and_b32_e32 v137, 0xffff0000, v139
	v_pk_mul_f32 v[74:75], v[74:75], v[132:133]
	v_pk_mul_f32 v[72:73], v[72:73], v[2:3]
	v_lshlrev_b32_e32 v2, 16, v134
	v_and_b32_e32 v3, 0xffff0000, v134
	v_lshlrev_b32_e32 v132, 16, v135
	v_and_b32_e32 v133, 0xffff0000, v135
	v_pk_mul_f32 v[118:119], v[118:119], v[156:157]
	v_pk_mul_f32 v[110:111], v[110:111], v[152:153]
	v_pk_mul_f32 v[102:103], v[102:103], v[148:149]
	v_pk_mul_f32 v[94:95], v[94:95], v[144:145]
	v_pk_mul_f32 v[86:87], v[86:87], v[140:141]
	v_pk_mul_f32 v[78:79], v[78:79], v[136:137]
	v_pk_mul_f32 v[70:71], v[70:71], v[132:133]
	v_pk_mul_f32 v[68:69], v[68:69], v[2:3]
	s_waitcnt vmcnt(7)
; __device__ __forceinline__ float bflo(unsigned w) { return __uint_as_float(w << 16); }
; __device__ __forceinline__ float bfhi(unsigned w) { return __uint_as_float(w & 0xffff0000u); }
;     __device__ __forceinline__ void mid(f32x4 (&acc)[2][2][4][2], const pg8::Unit& u, int wr, int wc, int fr, int fq) const {
;     ...
; #pragma unroll
;             for (int m = 0; m < 4; ++m)
; #pragma unroll
;                 for (int bj = 0; bj < 2; ++bj) {
;                     const u32x4 a = ga[m][bj];
;                     acc[ai][bj][m][0] = acc[ai][bj][m][0] * (f32x4){bflo(a.x), bfhi(a.x), bflo(a.y), bfhi(a.y)}; acc[ai][bj][m][1] = acc[ai][bj][m][1] * (f32x4){bflo(a.z), bfhi(a.z), bflo(a.w), bfhi(a.w)};
;                 }
;             asm volatile("" ::: "memory");
	v_lshlrev_b32_e32 v2, 16, v200
	v_and_b32_e32 v3, 0xffff0000, v200
	v_lshlrev_b32_e32 v132, 16, v201
	v_and_b32_e32 v133, 0xffff0000, v201
	v_pk_mul_f32 v[66:67], v[66:67], v[132:133]
	v_pk_mul_f32 v[64:65], v[64:65], v[2:3]
	v_lshlrev_b32_e32 v2, 16, v202
	v_and_b32_e32 v3, 0xffff0000, v202
	v_lshlrev_b32_e32 v132, 16, v203
	v_and_b32_e32 v133, 0xffff0000, v203
	v_pk_mul_f32 v[62:63], v[62:63], v[132:133]
	v_pk_mul_f32 v[60:61], v[60:61], v[2:3]
	s_waitcnt vmcnt(6)
	v_lshlrev_b32_e32 v2, 16, v204
	v_and_b32_e32 v3, 0xffff0000, v204
	v_lshlrev_b32_e32 v132, 16, v205
	v_and_b32_e32 v133, 0xffff0000, v205
	v_pk_mul_f32 v[58:59], v[58:59], v[132:133]
	v_pk_mul_f32 v[56:57], v[56:57], v[2:3]
	v_lshlrev_b32_e32 v2, 16, v206
	v_and_b32_e32 v3, 0xffff0000, v206
	v_lshlrev_b32_e32 v132, 16, v207
	v_and_b32_e32 v133, 0xffff0000, v207
	v_pk_mul_f32 v[54:55], v[54:55], v[132:133]
	v_pk_mul_f32 v[52:53], v[52:53], v[2:3]
	s_waitcnt vmcnt(5)
	v_lshlrev_b32_e32 v2, 16, v208
	v_and_b32_e32 v3, 0xffff0000, v208
	v_lshlrev_b32_e32 v132, 16, v209
	v_and_b32_e32 v133, 0xffff0000, v209
	v_pk_mul_f32 v[50:51], v[50:51], v[132:133]
	v_pk_mul_f32 v[48:49], v[48:49], v[2:3]
	v_lshlrev_b32_e32 v2, 16, v210
	v_and_b32_e32 v3, 0xffff0000, v210
	v_lshlrev_b32_e32 v132, 16, v211
	v_and_b32_e32 v133, 0xffff0000, v211
	v_pk_mul_f32 v[46:47], v[46:47], v[132:133]
	v_pk_mul_f32 v[44:45], v[44:45], v[2:3]
	s_waitcnt vmcnt(4)
	v_lshlrev_b32_e32 v2, 16, v212
	v_and_b32_e32 v3, 0xffff0000, v212
	v_lshlrev_b32_e32 v132, 16, v213
	v_and_b32_e32 v133, 0xffff0000, v213
	v_pk_mul_f32 v[42:43], v[42:43], v[132:133]
	v_pk_mul_f32 v[40:41], v[40:41], v[2:3]
	v_lshlrev_b32_e32 v2, 16, v214
	v_and_b32_e32 v3, 0xffff0000, v214
	v_lshlrev_b32_e32 v132, 16, v215
	v_and_b32_e32 v133, 0xffff0000, v215
	v_pk_mul_f32 v[38:39], v[38:39], v[132:133]
	v_pk_mul_f32 v[36:37], v[36:37], v[2:3]
	s_waitcnt vmcnt(3)
	v_lshlrev_b32_e32 v2, 16, v216
	v_and_b32_e32 v3, 0xffff0000, v216
	v_lshlrev_b32_e32 v132, 16, v217
	v_and_b32_e32 v133, 0xffff0000, v217
	v_pk_mul_f32 v[34:35], v[34:35], v[132:133]
	v_pk_mul_f32 v[32:33], v[32:33], v[2:3]
	v_lshlrev_b32_e32 v2, 16, v218
	v_and_b32_e32 v3, 0xffff0000, v218
	v_lshlrev_b32_e32 v132, 16, v219
	v_and_b32_e32 v133, 0xffff0000, v219
	v_pk_mul_f32 v[30:31], v[30:31], v[132:133]
	v_pk_mul_f32 v[28:29], v[28:29], v[2:3]
	s_waitcnt vmcnt(2)
	v_lshlrev_b32_e32 v2, 16, v168
	v_and_b32_e32 v3, 0xffff0000, v168
	v_lshlrev_b32_e32 v132, 16, v169
	v_and_b32_e32 v133, 0xffff0000, v169
	v_pk_mul_f32 v[26:27], v[26:27], v[132:133]
	v_pk_mul_f32 v[24:25], v[24:25], v[2:3]
	v_lshlrev_b32_e32 v2, 16, v170
	v_and_b32_e32 v3, 0xffff0000, v170
	v_lshlrev_b32_e32 v132, 16, v171
	v_and_b32_e32 v133, 0xffff0000, v171
	v_pk_mul_f32 v[22:23], v[22:23], v[132:133]
	v_pk_mul_f32 v[20:21], v[20:21], v[2:3]
	s_waitcnt vmcnt(1)
	v_lshlrev_b32_e32 v2, 16, v164
	v_and_b32_e32 v3, 0xffff0000, v164
	v_lshlrev_b32_e32 v132, 16, v165
	v_and_b32_e32 v133, 0xffff0000, v165
	v_pk_mul_f32 v[18:19], v[18:19], v[132:133]
	v_pk_mul_f32 v[16:17], v[16:17], v[2:3]
	v_lshlrev_b32_e32 v2, 16, v166
	v_and_b32_e32 v3, 0xffff0000, v166
	v_lshlrev_b32_e32 v132, 16, v167
	v_and_b32_e32 v133, 0xffff0000, v167
	v_pk_mul_f32 v[14:15], v[14:15], v[132:133]
	v_pk_mul_f32 v[12:13], v[12:13], v[2:3]
	s_waitcnt vmcnt(0)
	v_lshlrev_b32_e32 v2, 16, v160
	v_and_b32_e32 v3, 0xffff0000, v160
	v_lshlrev_b32_e32 v132, 16, v161
	v_and_b32_e32 v133, 0xffff0000, v161
	v_pk_mul_f32 v[10:11], v[10:11], v[132:133]
	v_pk_mul_f32 v[8:9], v[8:9], v[2:3]
	v_lshlrev_b32_e32 v2, 16, v162
	v_and_b32_e32 v3, 0xffff0000, v162
	v_lshlrev_b32_e32 v132, 16, v163
	v_and_b32_e32 v133, 0xffff0000, v163
	v_pk_mul_f32 v[6:7], v[6:7], v[132:133]
	v_pk_mul_f32 v[4:5], v[4:5], v[2:3]
	s_branch .LBB0_783
